# P0: three workgroup classes (blockIdx % 3) run the weight-item, x-row and rope parts in rotated orders so all three kinds of work are active chip-wide at once
# speedup vs baseline: 1.0084x; 1.0015x over previous
.LBB0_10:
	s_or_b64 exec, exec, s[2:3]
	s_load_dwordx16 s[72:87], s[0:1], 0x40
	v_readlane_b32 s0, v254, 5
	s_lshr_b32 s89, s0, 6
	v_readlane_b32 s0, v254, 9
	v_readlane_b32 s1, v254, 10
	v_readlane_b32 s2, v254, 11
	v_readlane_b32 s3, v254, 12
	s_cmp_lt_i32 s0, 1
	s_cselect_b64 s[2:3], -1, 0
	s_cmp_gt_i32 s1, 0
	s_cselect_b64 s[0:1], -1, 0
	v_writelane_b32 v254, s2, 31
	s_and_b64 s[6:7], s[2:3], s[0:1]
	s_andn2_b64 vcc, exec, s[6:7]
	v_and_b32_e32 v227, 63, v226
	v_writelane_b32 v254, s3, 32
	s_cbranch_vccnz .LBB0_183
	s_mul_hi_u32 s0, s88, 0x55555556
	s_mul_i32 s0, s0, 3
	s_sub_u32 s99, s88, s0
	s_cmp_eq_u32 s99, 0
	s_cbranch_scc1 .Lp0_front
	s_cmp_eq_u32 s99, 1
	s_cbranch_scc1 .LBB0_163
	s_mov_b32 s99, 3
	s_lshl_b32 s0, s88, 3
	s_add_i32 s8, s89, s0
	s_lshl_b32 s10, s90, 3
	s_branch .LBB0_158

.LBB0_158:
	s_cmp_eq_u32 s99, 5
	s_cbranch_scc1 .Lp0_done
	s_cmpk_gt_i32 s8, 0x3fff
	s_cbranch_scc1 .LBB0_163
	v_mbcnt_lo_u32_b32 v0, -1, 0
	v_mbcnt_hi_u32_b32 v0, -1, v0
	v_and_b32_e32 v1, 64, v0
	v_add_u32_e32 v1, 64, v1
	v_xor_b32_e32 v2, 1, v0
	v_cmp_lt_i32_e32 vcc, v2, v1
	s_ashr_i32 s9, s8, 31
	s_ashr_i32 s11, s10, 31
	v_cndmask_b32_e32 v2, v0, v2, vcc
	v_lshlrev_b32_e32 v6, 2, v2
	v_xor_b32_e32 v2, 2, v0
	v_cmp_lt_i32_e32 vcc, v2, v1
	s_lshl_b64 s[0:1], s[8:9], 11
	s_lshl_b64 s[2:3], s[8:9], 2
	v_cndmask_b32_e32 v2, v0, v2, vcc
	v_lshlrev_b32_e32 v7, 2, v2
	v_xor_b32_e32 v2, 4, v0
	v_cmp_lt_i32_e32 vcc, v2, v1
	s_lshl_b64 s[4:5], s[10:11], 2
	s_lshl_b64 s[12:13], s[10:11], 11
	v_cndmask_b32_e32 v2, v0, v2, vcc
	v_lshlrev_b32_e32 v8, 2, v2
	v_xor_b32_e32 v2, 8, v0
	v_cmp_lt_i32_e32 vcc, v2, v1
	v_readlane_b32 s16, v254, 13
	v_readlane_b32 s17, v254, 14
	v_cndmask_b32_e32 v2, v0, v2, vcc
	v_lshlrev_b32_e32 v9, 2, v2
	v_xor_b32_e32 v2, 16, v0
	v_cmp_lt_i32_e32 vcc, v2, v1
	v_mov_b32_e32 v3, 0
	v_readlane_b32 s18, v254, 15
	v_cndmask_b32_e32 v2, v0, v2, vcc
	v_lshlrev_b32_e32 v10, 2, v2
	v_xor_b32_e32 v2, 32, v0
	v_cmp_lt_i32_e32 vcc, v2, v1
	v_mov_b32_e32 v1, s1
	v_readlane_b32 s19, v254, 16
	v_cndmask_b32_e32 v0, v0, v2, vcc
	v_lshlrev_b32_e32 v11, 2, v0
	v_lshl_or_b32 v0, v227, 3, s0
	s_lshl_b64 s[0:1], s[8:9], 12
	s_add_u32 s0, s16, s0
	v_lshlrev_b32_e32 v2, 4, v227
	s_addc_u32 s1, s17, s1
	v_lshl_add_u64 v[4:5], s[0:1], 0, v[2:3]
	s_mov_b64 s[0:1], 0xc00
	v_cmp_eq_u32_e32 vcc, 0, v227
	v_lshl_add_u64 v[4:5], v[4:5], 0, s[0:1]
	s_lshl_b64 s[14:15], s[10:11], 12
	s_mov_b32 s9, 0x3500000
	v_readlane_b32 s20, v254, 17
	v_readlane_b32 s21, v254, 18
	v_readlane_b32 s22, v254, 19
	v_readlane_b32 s23, v254, 20
	v_readlane_b32 s24, v254, 21
	v_readlane_b32 s25, v254, 22
	v_readlane_b32 s26, v254, 23
	v_readlane_b32 s27, v254, 24
	v_readlane_b32 s28, v254, 25
	v_readlane_b32 s29, v254, 26
	v_readlane_b32 s30, v254, 27
	v_readlane_b32 s31, v254, 28
	s_branch .LBB0_161

.LBB0_163:
	s_cmp_eq_u32 s99, 2
	s_cbranch_scc1 .Lp0_done
	s_cmp_eq_u32 s99, 3
	s_cbranch_scc0 .Lp0_rope
	s_mov_b32 s99, 4

.Lp0_n1:
	s_cmp_eq_u32 s99, 4
	s_cbranch_scc0 .Lp0_done
	s_mov_b32 s99, 5
	s_branch .Lp0_front
